# XCD grid barrier: non-leader workgroups spin on the global generation word directly (one release hop fewer)
# baseline (speedup 1.0000x reference)
.LBB0_1181:
	s_or_b64 exec, exec, s[2:3]
	v_cvt_f32_u32_e32 v5, v3
	s_waitcnt vmcnt(0)
	v_readfirstlane_b32 s2, v4
	v_sub_u32_e32 v4, 0, v3
	v_rcp_iflag_f32_e32 v5, v5
	v_add_u32_e32 v6, s2, v0
	v_mul_f32_e32 v5, 0x4f7ffffe, v5
	v_cvt_u32_f32_e32 v5, v5
	v_mul_lo_u32 v0, v4, v5
	v_mul_hi_u32 v0, v5, v0
	v_add_u32_e32 v0, v5, v0
	v_mul_hi_u32 v0, v6, v0
	v_mul_lo_u32 v4, v0, v3
	v_sub_u32_e32 v4, v6, v4
	v_add_u32_e32 v5, 1, v0
	v_cmp_ge_u32_e32 vcc, v4, v3
	s_nop 1
	v_cndmask_b32_e32 v0, v0, v5, vcc
	v_sub_u32_e32 v5, v4, v3
	v_cndmask_b32_e32 v4, v4, v5, vcc
	v_add_u32_e32 v5, 1, v0
	v_cmp_ge_u32_e32 vcc, v4, v3
	v_add_u32_e32 v4, 1, v6
	s_nop 0
	v_cndmask_b32_e32 v0, v0, v5, vcc
	v_mul_lo_u32 v5, v3, v0
	v_add_u32_e32 v3, v5, v3
	v_cmp_ne_u32_e32 vcc, v4, v3
	s_and_saveexec_b64 s[2:3], vcc
	s_xor_b64 s[2:3], exec, s[2:3]
	s_cbranch_execz .LBB0_1195
	v_readlane_b32 s4, v252, 13
	v_readlane_b32 s5, v252, 14
	s_waitcnt lgkmcnt(0)
	s_nop 3
	global_load_dword v2, v1, s[4:5] sc1
	s_waitcnt vmcnt(0)
	v_cmp_eq_u32_e32 vcc, v2, v0
	s_and_saveexec_b64 s[4:5], vcc
	s_cbranch_execz .LBB0_1194
	s_mov_b32 s16, 1
	s_mov_b64 s[6:7], 0
	s_branch .LBB0_1185
